# second mixer group: the 32 workgroups that run the sample-stream attention units take no GLA chunk-local units; those are dealt over the other 224 workgroups (stride G-32)
# speedup vs baseline: 1.0315x; 1.0069x over previous
; #define AIN(i) arg_in(i)
; __device__ __forceinline__ void gla_a_unit(LAS unsigned char* lds, bf16* QKA, bf16* VA, const float* FA, unsigned char* ws, int xnrow0, float* DECB, int lchunk, int h,
;                                            const float* wgate, const float* bgate, int tid) {
;     const int lane = tid & 63, w = __builtin_amdgcn_readfirstlane(tid >> 6), r32 = lane & 31, hi = lane >> 5, g16 = lane >> 4, i16 = lane & 15;
;     const int gd = tid & 127, tq = tid >> 7;
;     LAS float* Bimg = (LAS float*)(lds + G_B); LAS float* FAi = (LAS float*)(lds + G_FA); LAS float* SEG = (LAS float*)(lds + G_SEG);
;     const int trrow = (g16 >> 1) * 4 + (i16 >> 2), trcol = (g16 & 1) * 16 + (i16 & 3) * 4;
;     const size_t row0 = (size_t)lchunk * 64; const int unit = lchunk * 4 + h;
;     u32x4 qv[2], kv[2];
; #pragma unroll
;     for (int i = 0; i < 2; ++i) { const int id = tid + 512 * i, row = id >> 4, ch = id & 15; const bf16* p = QKA + (row0 + row) * 1024 + h * 128 + ch * 8; qv[i] = *(const u32x4*)p; kv[i] = *(const u32x4*)(p + 512); }
;     if (tid < 256) *(LAS f32x4*)(FAi + tid * 4) = *(const f32x4*)(FA + row0 * 16 + tid * 4);
; #pragma unroll
;     for (int i = 0; i < 4; ++i) { const int id = tid + 512 * i, row = id >> 5, ch = id & 31; *(LAS u32x4*)(lds + G_VV + row * GVP + ch * 16) = *(const u32x4*)(VA + (row0 + row) * 1024 + h * 256 + ch * 8); }
;     __syncthreads();
;     {
;         float wg[16];
; #pragma unroll
;         for (int r = 0; r < 16; ++r) wg[r] = wgate[r * 512 + h * 128 + gd];
;         const float bg = bgate[h * 128 + gd];
;         float run = 0.f;
; #pragma unroll
;         for (int tt = 0; tt < 16; ++tt) { const int t = tq * 16 + tt; const LAS f32x4* fp = (const LAS f32x4*)(FAi + t * 16); float x = bg;
; #pragma unroll
;             for (int q = 0; q < 4; ++q) { const f32x4 f = fp[q]; x += f[0] * wg[4 * q] + f[1] * wg[4 * q + 1] + f[2] * wg[4 * q + 2] + f[3] * wg[4 * q + 3]; }
;             const float ls = fminf(x, 0.f) - __logf(1.0f + __expf(-fabsf(x))); run += ls * 0.0625f; Bimg[t * GBP + gd] = run;
; __global__ void __launch_bounds__(NTHREADS, 2) fwd_megakernel(Args a) {
;     ...
;             const int nun = (grp ? 264 : 256) * 4;
;             for (int u = G - 1 - bx; u < nun; u += G) gla_a_unit(lds, PB, PB + PBE, FA, (unsigned char*)H, row0, (float*)((unsigned char*)H + WS_DECB), u >> 2, u & 3, AIN(10), AIN(11), tid);
.LBB0_555:
	v_readlane_b32 s2, v251, 33
	v_writelane_b32 v250, s44, 7
	s_movk_i32 s0, 0x100
	s_waitcnt vmcnt(10)
	v_mov_b32_e32 v117, v201
	s_mov_b32 s32, s70
	s_cmpk_lg_i32 s64, 0x420
	s_cbranch_scc1 .Lgla_a_bal
	s_sub_i32 s32, s70, 32
	s_cmp_lt_i32 s2, s32
	s_cbranch_scc1 .Lgla_a_bal
	s_mov_b32 s2, s64
.Lgla_a_bal:
	s_cmp_ge_i32 s2, s64
	v_writelane_b32 v250, s45, 8
	s_barrier
	v_readlane_b32 s3, v251, 34
	s_cbranch_scc1 .LBB0_564
	v_readlane_b32 s68, v250, 7
	v_readlane_b32 s69, v250, 8
	s_add_u32 s4, s68, 0xad90000
	v_and_b32_e32 v10, 31, v117
	s_addc_u32 s5, s69, 0
	v_lshlrev_b32_e32 v2, 4, v10
	v_lshlrev_b32_e32 v4, 2, v117
	v_lshl_add_u64 v[106:107], s[4:5], 0, v[2:3]
	v_add_u32_e32 v11, 0, v2
	v_add_u32_e32 v2, 0x400, v117
	v_ashrrev_i32_e32 v5, 31, v4
	s_waitcnt vmcnt(9)
	v_ashrrev_i32_e32 v112, 5, v2
	v_add_u32_e32 v2, 0x600, v117
	v_lshl_add_u64 v[6:7], v[4:5], 2, s[68:69]
	s_mov_b64 s[2:3], 0x19490000
	v_ashrrev_i32_e32 v114, 5, v2
	v_ashrrev_i32_e32 v2, 3, v117
	v_lshl_add_u64 v[104:105], v[6:7], 0, s[2:3]
	v_and_b32_e32 v6, -16, v2
	s_movk_i32 s6, 0x210
	v_or_b32_e32 v2, 15, v2
	v_add_u32_e32 v9, 0x200, v117
	v_lshlrev_b32_e32 v32, 6, v2
	v_mul_lo_u32 v33, v2, s6
	v_ashrrev_i32_e32 v2, 8, v117
	v_cmp_lt_i32_e64 s[8:9], 0, v2
	v_cmp_lt_i32_e64 s[10:11], 1, v2
	v_cmp_lt_i32_e64 s[12:13], 2, v2
	v_cmp_lt_i32_e64 s[14:15], 3, v2
	v_ashrrev_i32_e32 v2, 8, v9
	v_readlane_b32 s7, v251, 55
	v_cmp_lt_i32_e64 s[20:21], 3, v2
	v_cmp_lt_i32_e64 s[22:23], 2, v2
	v_cmp_lt_i32_e64 s[24:25], 1, v2
	v_cmp_lt_i32_e64 s[26:27], 0, v2
	v_and_b32_e32 v2, 16, v117
	v_ashrrev_i32_e32 v102, 4, v9
	v_ashrrev_i32_e32 v110, 5, v9
	s_waitcnt vmcnt(8)
	v_add_u32_e32 v129, s7, v4
	v_cmp_gt_u32_e64 s[18:19], 16, v9
	v_and_or_b32 v2, v4, 12, v2
	v_lshrrev_b32_e32 v4, 3, v117
	v_bfe_u32 v9, v117, 2, 2
	v_and_or_b32 v4, v4, 4, v9
	v_bfe_u32 v9, v117, 5, 1
	v_lshlrev_b32_e32 v44, 4, v9
	v_lshlrev_b32_e32 v9, 2, v9
	v_or_b32_e32 v45, 2, v9
	v_cmp_gt_u32_e64 s[34:35], v45, v10
	v_or_b32_e32 v45, 3, v9
	v_cmp_gt_u32_e64 s[36:37], v45, v10
	v_or_b32_e32 v45, 8, v9
	v_cmp_gt_u32_e64 s[38:39], v45, v10
	v_or_b32_e32 v45, 9, v9
	v_cmp_gt_u32_e64 s[40:41], v45, v10
	v_or_b32_e32 v45, 10, v9
	v_cmp_gt_u32_e64 s[42:43], v45, v10
	v_or_b32_e32 v45, 11, v9
	v_cmp_gt_u32_e64 s[44:45], v45, v10
	v_or_b32_e32 v45, 16, v9
	v_cmp_gt_u32_e64 s[46:47], v45, v10
	v_or_b32_e32 v45, 17, v9
	v_cmp_gt_u32_e64 s[48:49], v45, v10
	v_or_b32_e32 v45, 18, v9
	v_cmp_gt_u32_e64 s[50:51], v45, v10
	v_or_b32_e32 v45, 19, v9
	v_and_b32_e32 v8, 15, v117
	v_cmp_gt_u32_e64 s[52:53], v45, v10
	v_or_b32_e32 v45, 24, v9
	v_ashrrev_i32_e32 v100, 4, v117
	v_lshlrev_b32_e32 v128, 6, v6
	v_mul_lo_u32 v17, v6, s6
	v_lshlrev_b32_e32 v6, 5, v8
	s_movk_i32 s28, 0x110
	v_cmp_gt_u32_e64 s[54:55], v45, v10
	v_or_b32_e32 v45, 25, v9
	v_and_b32_e32 v126, 0x7f, v117
	v_lshlrev_b32_e32 v5, 4, v117
	v_readlane_b32 s3, v251, 54
	v_add_u32_e32 v130, s7, v6
	v_readlane_b32 s7, v251, 56
	v_mul_lo_u32 v38, v100, s28
	v_mul_lo_u32 v41, v102, s28
	v_lshlrev_b32_e32 v2, 1, v2
	v_mad_u32_u24 v43, v10, s28, 0
	v_cmp_gt_u32_e64 s[28:29], v9, v10
	v_cmp_lt_u32_e64 s[30:31], v9, v10
	v_cmp_gt_u32_e64 s[56:57], v45, v10
	v_or_b32_e32 v45, 26, v9
	v_or_b32_e32 v9, 27, v9
	v_cmp_gt_i32_e32 vcc, s0, v117
	v_readlane_b32 s0, v251, 53
	v_ashrrev_i32_e32 v108, 5, v117
	s_movk_i32 s2, 0x240
	v_lshl_add_u32 v16, v126, 2, s3
	v_add_u32_e32 v34, s3, v6
	s_movk_i32 s3, 0x140
	v_add_u32_e32 v131, 0, v2
	v_cmp_gt_u32_e64 s[60:61], v9, v10
	v_add_u32_e32 v9, s7, v2
	v_and_b32_e32 v2, 0xf0, v5
	v_add_u32_e32 v127, s0, v5
	v_mul_lo_u32 v12, v108, s2
	v_mul_lo_u32 v13, v110, s2
	v_mul_lo_u32 v14, v112, s2
	v_mul_lo_u32 v15, v114, s2
	v_mul_lo_u32 v39, v100, s3
	v_mul_lo_u32 v42, v102, s3
	v_mul_u32_u24_e32 v132, 0x240, v4
	v_mad_u32_u24 v133, v4, s2, v207
	v_cmp_gt_u32_e64 s[58:59], v45, v10
	v_mul_u32_u24_e32 v10, 0x140, v4
	v_lshl_add_u64 v[4:5], s[68:69], 0, v[2:3]
	s_mov_b64 s[2:3], 0x8c90000
	v_and_b32_e32 v7, 63, v117
	v_lshl_add_u64 v[118:119], v[4:5], 0, s[2:3]
	v_readlane_b32 s2, v251, 31
	v_lshlrev_b32_e32 v2, 4, v7
	v_readlane_b32 s3, v251, 32
	v_mov_b32_e32 v7, v3
	v_lshlrev_b32_e32 v8, 4, v8
	v_lshl_add_u64 v[120:121], s[2:3], 0, v[2:3]
	v_readlane_b32 s2, v251, 35
	v_readlane_b32 s3, v251, 36
	v_or_b32_e32 v18, 64, v128
	v_or_b32_e32 v19, 0x80, v128
	v_lshl_add_u64 v[122:123], s[2:3], 0, v[6:7]
	v_readlane_b32 s2, v251, 33
	v_or_b32_e32 v20, 0xc0, v128
	v_or_b32_e32 v21, 0x100, v128
	v_or_b32_e32 v22, 0x140, v128
	v_or_b32_e32 v23, 0x180, v128
	v_or_b32_e32 v24, 0x1c0, v128
	v_or_b32_e32 v25, 0x200, v128
	v_or_b32_e32 v26, 0x240, v128
	v_or_b32_e32 v27, 0x280, v128
	v_or_b32_e32 v28, 0x2c0, v128
	v_or_b32_e32 v29, 0x300, v128
	v_or_b32_e32 v30, 0x340, v128
	v_or_b32_e32 v31, 0x380, v128
	v_add_u32_e32 v35, 0, v8
	v_add_u32_e32 v36, s7, v8
	v_mul_lo_u32 v37, v100, s6
	v_mul_lo_u32 v40, v102, s6
	v_readlane_b32 s3, v251, 34
	v_ashrrev_i32_e32 v101, 31, v100
	v_ashrrev_i32_e32 v103, 31, v102
	v_ashrrev_i32_e32 v109, 31, v108
	v_ashrrev_i32_e32 v111, 31, v110
	v_ashrrev_i32_e32 v113, 31, v112
	v_ashrrev_i32_e32 v115, 31, v114
	v_cmp_gt_u32_e64 s[16:17], 16, v117
	v_bfe_u32 v116, v117, 4, 2
	s_lshl_b64 s[88:89], s[62:63], 2
	v_add_u32_e32 v134, v11, v12
	v_add_u32_e32 v135, v11, v13
	v_add_u32_e32 v136, v11, v14
	v_add_u32_e32 v137, v11, v15
	v_add_u32_e32 v138, v16, v17
	v_add_u32_e32 v139, v16, v33
	v_add_u32_e32 v146, v34, v37
	v_add_u32_e32 v147, v35, v38
	v_add_u32_e32 v148, v36, v39
	v_add_u32_e32 v149, v34, v40
	v_add_u32_e32 v150, v35, v41
	v_add_u32_e32 v151, v36, v42
	v_add_u32_e32 v152, v43, v44
	v_lshlrev_b32_e32 v124, 1, v8
	v_add_u32_e32 v153, v9, v10
	v_add_u32_e32 v154, s0, v18
	v_add_u32_e32 v155, s0, v19
	v_add_u32_e32 v156, s0, v20
	v_add_u32_e32 v157, s0, v21
	v_add_u32_e32 v158, s0, v22
	v_add_u32_e32 v159, s0, v23
	v_add_u32_e32 v160, s0, v24
	v_add_u32_e32 v161, s0, v25
	v_add_u32_e32 v162, s0, v26
	v_add_u32_e32 v163, s0, v27
	v_add_u32_e32 v164, s0, v28
	v_add_u32_e32 v165, s0, v29
	v_add_u32_e32 v166, s0, v30
	v_add_u32_e32 v167, s0, v31
	v_add_u32_e32 v168, s0, v32
	s_mov_b32 s3, s2
	s_branch .LBB0_558
; #define LAS __attribute__((address_space(3)))
; __device__ __forceinline__ unsigned pk2(float lo, float hi) { return pg8::cvt_pk_bf16(lo, hi); }
; __device__ __forceinline__ float bflo(unsigned w) { return __uint_as_float(w << 16); }
; __device__ __forceinline__ float bfhi(unsigned w) { return __uint_as_float(w & 0xffff0000u); }
; __device__ __forceinline__ void gla_a_unit(LAS unsigned char* lds, bf16* QKA, bf16* VA, const float* FA, unsigned char* ws, int xnrow0, float* DECB, int lchunk, int h,
;                                            const float* wgate, const float* bgate, int tid) {
;     ...
;     for (int i = 0; i < 2; ++i) { const int id = tid + 512 * i, row = id >> 4, ch = id & 15;
;         f32x4 b0 = *(const LAS f32x4*)(Bimg + row * GBP + ch * 8), b1 = *(const LAS f32x4*)(Bimg + row * GBP + ch * 8 + 4);
;         f32x4 l0 = (f32x4){0.f, 0.f, 0.f, 0.f}, l1 = l0;
; #pragma unroll
;         for (int q = 0; q < 4; ++q) { const f32x4 s0v = *(const LAS f32x4*)(SEG + q * 128 + ch * 8), s1v = *(const LAS f32x4*)(SEG + q * 128 + ch * 8 + 4);
;             l0 += s0v; l1 += s1v; if (q < (row >> 4)) { b0 += s0v; b1 += s1v; } }
;         if (row == 0) { float* dp = DECB + (size_t)unit * 128 + ch * 8;
;             *(f32x4*)dp = (f32x4){__expf(l0[0]), __expf(l0[1]), __expf(l0[2]), __expf(l0[3])}; *(f32x4*)(dp + 4) = (f32x4){__expf(l1[0]), __expf(l1[1]), __expf(l1[2]), __expf(l1[3])}; }
;         const float bb[8] = {b0[0], b0[1], b0[2], b0[3], b1[0], b1[1], b1[2], b1[3]};
;         const unsigned qw[4] = {qv[i].x, qv[i].y, qv[i].z, qv[i].w}, kw[4] = {kv[i].x, kv[i].y, kv[i].z, kv[i].w};
;         unsigned oq[4], oi[4];
; #pragma unroll
;         for (int e = 0; e < 4; ++e) { const float q0 = bflo(qw[e]), q1 = bfhi(qw[e]), k0 = bflo(kw[e]), k1 = bfhi(kw[e]);
;             const float e0 = __expf(bb[2 * e]), e1 = __expf(bb[2 * e + 1]), n0 = __expf(-bb[2 * e]), n1 = __expf(-bb[2 * e + 1]);
;             oq[e] = pk2(q0 * e0, q1 * e1); oi[e] = pk2(k0 * n0, k1 * n1); }
;         const u32x4 qd = (u32x4){oq[0], oq[1], oq[2], oq[3]};
;         *(LAS u32x4*)(lds + G_QD + row * GP + ch * 16) = qd;
;         *(LAS u32x4*)(lds + G_KI + row * GP + ch * 16) = (u32x4){oi[0], oi[1], oi[2], oi[3]};
;         *(LAS u32x4*)(lds + G_KT + row * GKTP + ch * 16) = (u32x4){oi[0], oi[1], oi[2], oi[3]};
;         *(u32x4*)(QKA + (row0 + row) * 1024 + h * 128 + ch * 8) = qd; }
.LBB0_557:
	s_or_b64 exec, exec, s[62:63]
	s_waitcnt lgkmcnt(7)
	v_pk_add_f32 v[48:49], v[44:45], v[48:49]
	s_waitcnt lgkmcnt(6)
	v_pk_add_f32 v[28:29], v[24:25], v[28:29]
	v_cndmask_b32_e64 v45, v45, v49, s[26:27]
	v_cndmask_b32_e64 v44, v44, v48, s[26:27]
	s_waitcnt lgkmcnt(5)
	v_pk_add_f32 v[40:41], v[44:45], v[40:41]
	v_cndmask_b32_e64 v25, v25, v29, s[26:27]
	v_cndmask_b32_e64 v24, v24, v28, s[26:27]
	v_cndmask_b32_e64 v41, v45, v41, s[24:25]
	v_cndmask_b32_e64 v40, v44, v40, s[24:25]
	v_pk_add_f32 v[30:31], v[26:27], v[30:31]
	s_waitcnt lgkmcnt(4)
	v_pk_add_f32 v[20:21], v[24:25], v[20:21]
	s_waitcnt lgkmcnt(3)
	v_pk_add_f32 v[36:37], v[40:41], v[36:37]
	v_cndmask_b32_e64 v27, v27, v31, s[26:27]
	v_cndmask_b32_e64 v26, v26, v30, s[26:27]
	v_cndmask_b32_e64 v21, v25, v21, s[24:25]
	v_cndmask_b32_e64 v20, v24, v20, s[24:25]
	v_cndmask_b32_e64 v37, v41, v37, s[22:23]
	v_cndmask_b32_e64 v36, v40, v36, s[22:23]
	v_pk_add_f32 v[22:23], v[26:27], v[22:23]
	s_waitcnt lgkmcnt(2)
	v_pk_add_f32 v[16:17], v[20:21], v[16:17]
	s_waitcnt lgkmcnt(1)
	v_pk_add_f32 v[32:33], v[36:37], v[32:33]
	v_cndmask_b32_e64 v23, v27, v23, s[24:25]
	v_cndmask_b32_e64 v22, v26, v22, s[24:25]
	v_cndmask_b32_e64 v17, v21, v17, s[22:23]
	v_cndmask_b32_e64 v16, v20, v16, s[22:23]
	v_cndmask_b32_e64 v33, v37, v33, s[20:21]
	v_cndmask_b32_e64 v32, v36, v32, s[20:21]
	v_pk_add_f32 v[18:19], v[22:23], v[18:19]
	s_waitcnt lgkmcnt(0)
	v_pk_add_f32 v[12:13], v[16:17], v[12:13]
	v_pk_add_f32 v[50:51], v[46:47], v[50:51]
	v_cndmask_b32_e64 v19, v23, v19, s[22:23]
	v_cndmask_b32_e64 v18, v22, v18, s[22:23]
	v_cndmask_b32_e64 v20, v17, v13, s[20:21]
	v_cndmask_b32_e64 v21, v16, v12, s[20:21]
	v_mul_f32_e32 v12, 0x3fb8aa3b, v32
	v_mul_f32_e32 v13, 0x3fb8aa3b, v33
	v_cndmask_b32_e64 v47, v47, v51, s[26:27]
	v_cndmask_b32_e64 v46, v46, v50, s[26:27]
	v_pk_add_f32 v[14:15], v[18:19], v[14:15]
	v_exp_f32_e32 v12, v12
	v_exp_f32_e32 v13, v13
	v_pk_add_f32 v[42:43], v[46:47], v[42:43]
	v_cndmask_b32_e64 v19, v19, v15, s[20:21]
	v_cndmask_b32_e64 v18, v18, v14, s[20:21]
	v_mul_f32_e32 v14, 0xbfb8aa3b, v32
	v_mul_f32_e32 v15, 0xbfb8aa3b, v33
	v_cndmask_b32_e64 v43, v47, v43, s[24:25]
	v_cndmask_b32_e64 v42, v46, v42, s[24:25]
	v_exp_f32_e32 v14, v14
	v_exp_f32_e32 v15, v15
	v_pk_add_f32 v[38:39], v[42:43], v[38:39]
	v_lshlrev_b32_e32 v16, 16, v8
	v_and_b32_e32 v17, 0xffff0000, v8
	v_cndmask_b32_e64 v39, v43, v39, s[22:23]
	v_cndmask_b32_e64 v38, v42, v38, s[22:23]
	v_pk_mul_f32 v[12:13], v[12:13], v[16:17]
	v_pk_add_f32 v[34:35], v[38:39], v[34:35]
	v_cvt_pk_bf16_f32 v8, v12, v13
	v_lshlrev_b32_e32 v12, 16, v4
	v_and_b32_e32 v13, 0xffff0000, v4
	v_cndmask_b32_e64 v2, v39, v35, s[20:21]
	v_cndmask_b32_e64 v34, v38, v34, s[20:21]
	v_pk_mul_f32 v[12:13], v[14:15], v[12:13]
	v_mul_f32_e32 v14, 0xbfb8aa3b, v34
	v_cvt_pk_bf16_f32 v4, v12, v13
	v_mul_f32_e32 v12, 0x3fb8aa3b, v34
	v_mul_f32_e32 v13, 0x3fb8aa3b, v2
	v_exp_f32_e32 v12, v12
	v_exp_f32_e32 v13, v13
	v_mul_f32_e32 v2, 0xbfb8aa3b, v2
	v_exp_f32_e32 v14, v14
	v_exp_f32_e32 v15, v2
	v_lshlrev_b32_e32 v16, 16, v9
	v_and_b32_e32 v17, 0xffff0000, v9
	v_pk_mul_f32 v[12:13], v[12:13], v[16:17]
	v_mul_f32_e32 v2, 0x3fb8aa3b, v21
	v_cvt_pk_bf16_f32 v9, v12, v13
	v_lshlrev_b32_e32 v12, 16, v5
	v_and_b32_e32 v13, 0xffff0000, v5
	v_pk_mul_f32 v[12:13], v[14:15], v[12:13]
	v_lshlrev_b32_e32 v16, 16, v10
	v_cvt_pk_bf16_f32 v5, v12, v13
	v_exp_f32_e32 v12, v2
	v_mul_f32_e32 v2, 0x3fb8aa3b, v20
	v_exp_f32_e32 v13, v2
	v_mul_f32_e32 v2, 0xbfb8aa3b, v21
	v_exp_f32_e32 v14, v2
	v_mul_f32_e32 v2, 0xbfb8aa3b, v20
	v_exp_f32_e32 v15, v2
	v_and_b32_e32 v17, 0xffff0000, v10
	v_pk_mul_f32 v[12:13], v[12:13], v[16:17]
	v_mul_f32_e32 v2, 0x3fb8aa3b, v18
	v_cvt_pk_bf16_f32 v10, v12, v13
	v_lshlrev_b32_e32 v12, 16, v6
	v_and_b32_e32 v13, 0xffff0000, v6
	v_pk_mul_f32 v[12:13], v[14:15], v[12:13]
	v_lshlrev_b32_e32 v16, 16, v11
	v_cvt_pk_bf16_f32 v6, v12, v13
	v_exp_f32_e32 v12, v2
	v_mul_f32_e32 v2, 0x3fb8aa3b, v19
	v_exp_f32_e32 v13, v2
	v_mul_f32_e32 v2, 0xbfb8aa3b, v18
	v_exp_f32_e32 v14, v2
	v_mul_f32_e32 v2, 0xbfb8aa3b, v19
	v_exp_f32_e32 v15, v2
	v_and_b32_e32 v17, 0xffff0000, v11
	v_pk_mul_f32 v[12:13], v[12:13], v[16:17]
	s_and_b32 s6, s2, 0xffffffc0
	v_cvt_pk_bf16_f32 v11, v12, v13
	v_lshlrev_b32_e32 v12, 16, v7
	v_and_b32_e32 v13, 0xffff0000, v7
	v_pk_mul_f32 v[12:13], v[14:15], v[12:13]
	v_add_u32_e32 v2, s6, v131
	v_cvt_pk_bf16_f32 v7, v12, v13
	ds_write_b128 v150, v[8:11]
	ds_write_b128 v150, v[4:7] offset:17408
	ds_write_b128 v151, v[4:7]
	global_store_dwordx4 v[60:61], v[8:11], off
	s_waitcnt lgkmcnt(0)
	s_barrier
; #define LAS __attribute__((address_space(3)))
; __device__ __forceinline__ void gla_a_unit(LAS unsigned char* lds, bf16* QKA, bf16* VA, const float* FA, unsigned char* ws, int xnrow0, float* DECB, int lchunk, int h,
;                                            const float* wgate, const float* bgate, int tid) {
;     ...
;     bf16x8 vvf[4];
; #pragma unroll
;     for (int kc = 0; kc < 4; ++kc) { LAS const unsigned char* p = lds + G_VV + (16 * kc + trrow) * GVP + (32 * w + trcol) * 2; vvf[kc] = cat8(tr16(p), tr16(p + 8 * GVP)); }
;     f32x16 s00, s01, s11;
; #pragma unroll
;     for (int r = 0; r < 16; ++r) { s00[r] = 0.f; s01[r] = 0.f; s11[r] = 0.f; }
; #pragma unroll
;     for (int s = 0; s < 8; ++s) {
;         const bf16x8 a0 = *(const LAS bf16x8*)(lds + G_KI + r32 * GP + (16 * s + 8 * hi) * 2), a1 = *(const LAS bf16x8*)(lds + G_KI + (32 + r32) * GP + (16 * s + 8 * hi) * 2);
;         const bf16x8 b0 = *(const LAS bf16x8*)(lds + G_QD + r32 * GP + (16 * s + 8 * hi) * 2), b1 = *(const LAS bf16x8*)(lds + G_QD + (32 + r32) * GP + (16 * s + 8 * hi) * 2);
;         s00 = __builtin_amdgcn_mfma_f32_32x32x16_bf16(a0, b0, s00, 0, 0, 0); s01 = __builtin_amdgcn_mfma_f32_32x32x16_bf16(a0, b1, s01, 0, 0, 0); s11 = __builtin_amdgcn_mfma_f32_32x32x16_bf16(a1, b1, s11, 0, 0, 0);
;     }
; #pragma unroll
;     for (int r = 0; r < 16; ++r) if (crow(r, hi) > r32) { s00[r] = 0.f; s11[r] = 0.f; }
;     const bf16x8 p00a = pack8(s00, 0), p00b = pack8(s00, 8), p01a = pack8(s01, 0), p01b = pack8(s01, 8), p11a = pack8(s11, 0), p11b = pack8(s11, 8);
;     f32x16 oT0, oT1;
; #pragma unroll
;     for (int r = 0; r < 16; ++r) { oT0[r] = 0.f; oT1[r] = 0.f; }
;     oT0 = __builtin_amdgcn_mfma_f32_32x32x16_bf16(vvf[0], p00a, oT0, 0, 0, 0); oT0 = __builtin_amdgcn_mfma_f32_32x32x16_bf16(vvf[1], p00b, oT0, 0, 0, 0);
;     oT1 = __builtin_amdgcn_mfma_f32_32x32x16_bf16(vvf[0], p01a, oT1, 0, 0, 0); oT1 = __builtin_amdgcn_mfma_f32_32x32x16_bf16(vvf[1], p01b, oT1, 0, 0, 0);
;     oT1 = __builtin_amdgcn_mfma_f32_32x32x16_bf16(vvf[2], p11a, oT1, 0, 0, 0); oT1 = __builtin_amdgcn_mfma_f32_32x32x16_bf16(vvf[3], p11b, oT1, 0, 0, 0);
; __global__ void __launch_bounds__(NTHREADS, 2) fwd_megakernel(Args a) {
;     ...
;             for (int u = G - 1 - bx; u < nun; u += G) gla_a_unit(lds, PB, PB + PBE, FA, (unsigned char*)H, row0, (float*)((unsigned char*)H + WS_DECB), u >> 2, u & 3, AIN(10), AIN(11), tid);
	ds_read_b128 v[36:39], v152 offset:17408
	ds_read_b128 v[4:7], v152
	s_waitcnt lgkmcnt(0)
	v_mfma_f32_32x32x16_bf16 v[20:35], v[36:39], v[4:7], 0
	ds_read_b128 v[4:7], v152 offset:26112
	ds_read_b128 v[40:43], v152 offset:8704
	ds_read_b128 v[52:55], v152 offset:17440
	ds_read_b128 v[44:47], v152 offset:32
	s_ashr_i32 s64, s2, 6
	s_lshl_b32 s2, s64, 3
	s_ashr_i32 s6, s2, 31
	s_add_u32 s2, s82, s2
	s_addc_u32 s6, s83, s6
	s_waitcnt lgkmcnt(2)
	v_mfma_f32_32x32x16_bf16 v[4:19], v[4:7], v[40:43], 0
	s_lshl_b32 s78, s78, 1
	v_mov_b32_e32 v125, v3
	s_ashr_i32 s65, s64, 31
	s_add_i32 s3, s3, s32
	s_mov_b32 s70, s68
	s_waitcnt lgkmcnt(0)
	v_mfma_f32_32x32x16_bf16 v[20:35], v[52:55], v[44:47], v[20:35]
	ds_read_b128 v[44:47], v152 offset:26144
	ds_read_b128 v[56:59], v152 offset:8736
	s_waitcnt lgkmcnt(0)
	v_mfma_f32_32x32x16_bf16 v[4:19], v[44:47], v[56:59], v[4:19]
	ds_read_b128 v[60:63], v152 offset:17472
	ds_read_b128 v[44:47], v152 offset:64
	s_waitcnt lgkmcnt(0)
	v_mfma_f32_32x32x16_bf16 v[20:35], v[60:63], v[44:47], v[20:35]
	ds_read_b128 v[44:47], v152 offset:26176
	ds_read_b128 v[64:67], v152 offset:8768
	s_waitcnt lgkmcnt(0)
	v_mfma_f32_32x32x16_bf16 v[4:19], v[44:47], v[64:67], v[4:19]
	ds_read_b128 v[68:71], v152 offset:17504
	ds_read_b128 v[44:47], v152 offset:96
	s_waitcnt lgkmcnt(0)
	v_mfma_f32_32x32x16_bf16 v[20:35], v[68:71], v[44:47], v[20:35]
	ds_read_b128 v[44:47], v152 offset:26208
	ds_read_b128 v[72:75], v152 offset:8800
	s_waitcnt lgkmcnt(0)
	v_mfma_f32_32x32x16_bf16 v[4:19], v[44:47], v[72:75], v[4:19]
	ds_read_b128 v[76:79], v152 offset:17536
	ds_read_b128 v[44:47], v152 offset:128
	s_waitcnt lgkmcnt(0)
	v_mfma_f32_32x32x16_bf16 v[20:35], v[76:79], v[44:47], v[20:35]
	ds_read_b128 v[44:47], v152 offset:26240
	ds_read_b128 v[80:83], v152 offset:8832
	s_waitcnt lgkmcnt(0)
	v_mfma_f32_32x32x16_bf16 v[4:19], v[44:47], v[80:83], v[4:19]
	ds_read_b128 v[170:173], v152 offset:17568
	ds_read_b128 v[44:47], v152 offset:160
	s_waitcnt lgkmcnt(0)
	v_mfma_f32_32x32x16_bf16 v[20:35], v[170:173], v[44:47], v[20:35]
	ds_read_b128 v[44:47], v152 offset:26272
	ds_read_b128 v[174:177], v152 offset:8864
	s_waitcnt lgkmcnt(0)
	v_mfma_f32_32x32x16_bf16 v[4:19], v[44:47], v[174:177], v[4:19]
	ds_read_b128 v[182:185], v152 offset:17600
	ds_read_b128 v[44:47], v152 offset:192
	s_waitcnt lgkmcnt(0)
	v_mfma_f32_32x32x16_bf16 v[20:35], v[182:185], v[44:47], v[20:35]
	ds_read_b128 v[44:47], v152 offset:26304
	ds_read_b128 v[186:189], v152 offset:8896
	s_waitcnt lgkmcnt(0)
	v_mfma_f32_32x32x16_bf16 v[4:19], v[44:47], v[186:189], v[4:19]
	ds_read_b128 v[190:193], v152 offset:17632
	ds_read_b128 v[44:47], v152 offset:224
	s_waitcnt lgkmcnt(0)
	v_mfma_f32_32x32x16_bf16 v[20:35], v[190:193], v[44:47], v[20:35]
	ds_read_b128 v[44:47], v152 offset:26336
	ds_read_b128 v[210:213], v152 offset:8928
	s_waitcnt lgkmcnt(0)
	v_mfma_f32_32x32x16_bf16 v[4:19], v[44:47], v[210:213], v[4:19]
	v_mfma_f32_32x32x16_bf16 v[36:51], v[36:39], v[40:43], 0
	v_mfma_f32_32x32x16_bf16 v[36:51], v[52:55], v[56:59], v[36:51]
	v_add_u32_e32 v52, v2, v132
	v_add_u32_e32 v2, v2, v133
	ds_read_b64_tr_b16 v[96:97], v52 offset:34816
	ds_read_b64_tr_b16 v[98:99], v52 offset:39424
	ds_read_b64_tr_b16 v[88:89], v52 offset:44032
	ds_read_b64_tr_b16 v[90:91], v52 offset:48640
	ds_read_b64_tr_b16 v[92:93], v52 offset:53248
	ds_read_b64_tr_b16 v[94:95], v52 offset:57856
	ds_read_b64_tr_b16 v[84:85], v52 offset:62464
	ds_read_b64_tr_b16 v[86:87], v2 offset:57856
	v_cndmask_b32_e64 v2, v20, 0, s[28:29]
	v_cndmask_b32_e64 v52, v4, 0, s[28:29]
	v_mfma_f32_32x32x16_bf16 v[36:51], v[60:63], v[64:67], v[36:51]
	v_cndmask_b32_e64 v2, v2, v20, s[30:31]
	v_cndmask_b32_e64 v20, 0, v21, s[30:31]
	v_cndmask_b32_e64 v21, v25, 0, s[40:41]
	v_cndmask_b32_e64 v25, v29, 0, s[48:49]
	v_mfma_f32_32x32x16_bf16 v[36:51], v[68:71], v[72:75], v[36:51]
	v_cndmask_b32_e64 v69, 0, v5, s[30:31]
	v_cndmask_b32_e64 v5, v22, 0, s[34:35]
	v_cndmask_b32_e64 v70, v6, 0, s[34:35]
	v_cndmask_b32_e64 v6, v23, 0, s[36:37]
	v_cndmask_b32_e64 v71, v7, 0, s[36:37]
	v_cndmask_b32_e64 v7, v24, 0, s[38:39]
	v_cndmask_b32_e64 v22, v26, 0, s[42:43]
	v_mfma_f32_32x32x16_bf16 v[36:51], v[76:79], v[80:83], v[36:51]
	v_cndmask_b32_e64 v23, v27, 0, s[44:45]
	v_cndmask_b32_e64 v68, v52, v4, s[30:31]
	v_cvt_pk_bf16_f32 v4, v2, v20
	v_cvt_pk_bf16_f32 v5, v5, v6
	v_cvt_pk_bf16_f32 v6, v7, v21
	v_cvt_pk_bf16_f32 v7, v22, v23
	v_cndmask_b32_e64 v24, v28, 0, s[46:47]
	v_mfma_f32_32x32x16_bf16 v[36:51], v[170:173], v[174:177], v[36:51]
	v_cndmask_b32_e64 v26, v30, 0, s[50:51]
	v_cndmask_b32_e64 v27, v31, 0, s[52:53]
	v_cndmask_b32_e64 v28, v32, 0, s[54:55]
	v_cndmask_b32_e64 v2, v33, 0, s[56:57]
	v_cndmask_b32_e64 v20, v35, 0, s[60:61]
	v_mfma_f32_32x32x16_bf16 v[36:51], v[182:185], v[186:189], v[36:51]
	v_mfma_f32_32x32x16_bf16 v[36:51], v[190:193], v[210:213], v[36:51]
	s_waitcnt lgkmcnt(6)
	v_mfma_f32_32x32x16_bf16 v[52:67], v[96:99], v[4:7], 0
	v_cndmask_b32_e64 v7, v34, 0, s[58:59]
	v_cvt_pk_bf16_f32 v4, v24, v25
	v_cvt_pk_bf16_f32 v5, v26, v27
	v_cvt_pk_bf16_f32 v6, v28, v2
	v_cvt_pk_bf16_f32 v7, v7, v20
	v_cndmask_b32_e64 v2, v8, 0, s[38:39]
	v_cndmask_b32_e64 v8, v9, 0, s[40:41]
	s_waitcnt lgkmcnt(4)
; #define LAS __attribute__((address_space(3)))
; __device__ __forceinline__ bf16x8 cat8(s16x4 a, s16x4 b) { return (bf16x8){a[0], a[1], a[2], a[3], b[0], b[1], b[2], b[3]}; }
; __device__ __forceinline__ bf16x8 pack8(const f32x16& v, int o) { u32x4 w; w.x = pk2(v[o], v[o + 1]); w.y = pk2(v[o + 2], v[o + 3]); w.z = pk2(v[o + 4], v[o + 5]); w.w = pk2(v[o + 6], v[o + 7]); return __builtin_bit_cast(bf16x8, w); }
; __device__ __forceinline__ bf16* ub_slot(unsigned char* ybase, int unit, int) { return (bf16*)ybase + (size_t)unit * 32768; }
; __device__ __forceinline__ void gla_a_unit(LAS unsigned char* lds, bf16* QKA, bf16* VA, const float* FA, unsigned char* ws, int xnrow0, float* DECB, int lchunk, int h,
;                                            const float* wgate, const float* bgate, int tid) {
;     ...
;     oT0 = __builtin_amdgcn_mfma_f32_32x32x16_bf16(vvf[0], p00a, oT0, 0, 0, 0); oT0 = __builtin_amdgcn_mfma_f32_32x32x16_bf16(vvf[1], p00b, oT0, 0, 0, 0);
;     oT1 = __builtin_amdgcn_mfma_f32_32x32x16_bf16(vvf[0], p01a, oT1, 0, 0, 0); oT1 = __builtin_amdgcn_mfma_f32_32x32x16_bf16(vvf[1], p01b, oT1, 0, 0, 0);
;     oT1 = __builtin_amdgcn_mfma_f32_32x32x16_bf16(vvf[2], p11a, oT1, 0, 0, 0); oT1 = __builtin_amdgcn_mfma_f32_32x32x16_bf16(vvf[3], p11b, oT1, 0, 0, 0);
;     { bf16* p0 = VA + (row0 + (2 * w) * 4 + g16) * 1024 + h * 256 + i16 * 16; bf16* p1 = p0 + 4 * 1024;
;       *(u32x4*)p0 = __builtin_bit_cast(u32x4, pack8(oT0, 0)); *(u32x4*)(p0 + 8) = __builtin_bit_cast(u32x4, pack8(oT0, 8));
;       *(u32x4*)p1 = __builtin_bit_cast(u32x4, pack8(oT1, 0)); *(u32x4*)(p1 + 8) = __builtin_bit_cast(u32x4, pack8(oT1, 8)); }
;     bf16* up = ub_slot(ws, unit, xnrow0) + (size_t)w * 4096 + lane * 8;
; #pragma unroll
;     for (int db = 0; db < 4; ++db) { f32x16 uacc;
; #pragma unroll
;         for (int r = 0; r < 16; ++r) uacc[r] = 0.f;
; #pragma unroll
;         for (int kc = 0; kc < 4; ++kc) { LAS const unsigned char* p = lds + G_KT + (16 * kc + trrow) * GKTP + (32 * db + trcol) * 2;
;             uacc = __builtin_amdgcn_mfma_f32_32x32x16_bf16(cat8(tr16(p), tr16(p + 8 * GKTP)), vvf[kc], uacc, 0, 0, 0); }
;         *(u32x4*)(up + (db * 2) * 512) = __builtin_bit_cast(u32x4, pack8(uacc, 0)); *(u32x4*)(up + (db * 2 + 1) * 512) = __builtin_bit_cast(u32x4, pack8(uacc, 8)); }
	v_mfma_f32_32x32x16_bf16 v[52:67], v[88:91], v[4:7], v[52:67]
	s_nop 0
	v_cvt_pk_bf16_f32 v4, v36, v37
	v_cvt_pk_bf16_f32 v5, v38, v39
	v_cvt_pk_bf16_f32 v6, v40, v41
	v_cvt_pk_bf16_f32 v7, v42, v43
	v_cndmask_b32_e64 v9, v10, 0, s[42:43]
	v_cndmask_b32_e64 v10, v11, 0, s[44:45]
	v_cndmask_b32_e64 v11, v12, 0, s[46:47]
	v_mfma_f32_32x32x16_bf16 v[20:35], v[96:99], v[4:7], 0
	v_cvt_pk_bf16_f32 v4, v44, v45
	v_cvt_pk_bf16_f32 v5, v46, v47
	v_cvt_pk_bf16_f32 v6, v48, v49
	v_cvt_pk_bf16_f32 v7, v50, v51
	v_cndmask_b32_e64 v12, v13, 0, s[48:49]
	v_cndmask_b32_e64 v13, v14, 0, s[50:51]
	v_cndmask_b32_e64 v14, v15, 0, s[52:53]
	v_mfma_f32_32x32x16_bf16 v[20:35], v[88:91], v[4:7], v[20:35]
	v_cvt_pk_bf16_f32 v4, v68, v69
	v_cvt_pk_bf16_f32 v5, v70, v71
	v_cvt_pk_bf16_f32 v6, v2, v8
	v_cvt_pk_bf16_f32 v7, v9, v10
	v_cndmask_b32_e64 v15, v16, 0, s[54:55]
	v_cndmask_b32_e64 v2, v17, 0, s[56:57]
	v_cndmask_b32_e64 v8, v19, 0, s[60:61]
	s_waitcnt lgkmcnt(2)
	v_mfma_f32_32x32x16_bf16 v[20:35], v[92:95], v[4:7], v[20:35]
	v_cndmask_b32_e64 v7, v18, 0, s[58:59]
	v_cvt_pk_bf16_f32 v4, v11, v12
	v_cvt_pk_bf16_f32 v5, v13, v14
	v_cvt_pk_bf16_f32 v6, v15, v2
	v_cvt_pk_bf16_f32 v7, v7, v8
	v_mov_b32_e32 v13, s6
	v_or_b32_e32 v12, s2, v116
	s_waitcnt lgkmcnt(0)
	v_mfma_f32_32x32x16_bf16 v[20:35], v[84:87], v[4:7], v[20:35]
	ds_read_b64_tr_b16 v[4:5], v153
	ds_read_b64_tr_b16 v[6:7], v153 offset:2560
	s_lshl_b64 s[6:7], s[64:65], 13
	s_mov_b32 s64, s69
	s_cmp_ge_i32 s3, s69
	s_waitcnt lgkmcnt(0)
	v_mfma_f32_32x32x16_bf16 v[68:83], v[4:7], v[96:99], 0
	ds_read_b64_tr_b16 v[4:5], v153 offset:5120
	ds_read_b64_tr_b16 v[6:7], v153 offset:7680
	s_waitcnt lgkmcnt(0)
	v_mfma_f32_32x32x16_bf16 v[68:83], v[4:7], v[88:91], v[68:83]
	ds_read_b64_tr_b16 v[4:5], v153 offset:10240
	ds_read_b64_tr_b16 v[6:7], v153 offset:12800
	ds_read_b64_tr_b16 v[8:9], v153 offset:15360
	ds_read_b64_tr_b16 v[10:11], v153 offset:17920
	s_waitcnt lgkmcnt(2)
	v_mfma_f32_32x32x16_bf16 v[68:83], v[4:7], v[92:95], v[68:83]
	ds_read_b64_tr_b16 v[4:5], v153 offset:64
	ds_read_b64_tr_b16 v[6:7], v153 offset:2624
	s_waitcnt lgkmcnt(0)
	v_mfma_f32_32x32x16_bf16 v[36:51], v[4:7], v[96:99], 0
	v_cvt_pk_bf16_f32 v4, v52, v53
	v_cvt_pk_bf16_f32 v5, v54, v55
	v_cvt_pk_bf16_f32 v6, v56, v57
	v_cvt_pk_bf16_f32 v7, v58, v59
	v_mfma_f32_32x32x16_bf16 v[68:83], v[8:11], v[84:87], v[68:83]
	v_lshlrev_b64 v[8:9], 11, v[12:13]
	v_lshl_add_u64 v[8:9], s[4:5], 0, v[8:9]
	v_lshl_add_u64 v[12:13], v[8:9], 0, s[78:79]
	ds_read_b64_tr_b16 v[8:9], v153 offset:5184
	ds_read_b64_tr_b16 v[10:11], v153 offset:7744
	v_lshl_add_u64 v[16:17], v[12:13], 0, v[124:125]
	ds_read_b64_tr_b16 v[12:13], v153 offset:10304
	ds_read_b64_tr_b16 v[14:15], v153 offset:12864
	global_store_dwordx4 v[16:17], v[4:7], off
	s_waitcnt lgkmcnt(2)
	v_mfma_f32_32x32x16_bf16 v[36:51], v[8:11], v[88:91], v[36:51]
	ds_read_b64_tr_b16 v[8:9], v153 offset:15424
	ds_read_b64_tr_b16 v[10:11], v153 offset:17984
	v_cvt_pk_bf16_f32 v4, v60, v61
	v_cvt_pk_bf16_f32 v5, v62, v63
	v_cvt_pk_bf16_f32 v6, v64, v65
	v_cvt_pk_bf16_f32 v7, v66, v67
	global_store_dwordx4 v[16:17], v[4:7], off offset:16
	v_add_co_u32_e64 v52, s[62:63], s96, v16
	s_waitcnt lgkmcnt(2)
	v_mfma_f32_32x32x16_bf16 v[36:51], v[12:15], v[92:95], v[36:51]
	v_cvt_pk_bf16_f32 v4, v20, v21
	v_cvt_pk_bf16_f32 v5, v22, v23
	v_cvt_pk_bf16_f32 v6, v24, v25
	v_cvt_pk_bf16_f32 v7, v26, v27
	v_addc_co_u32_e64 v53, s[62:63], 0, v17, s[62:63]
	v_cvt_pk_bf16_f32 v20, v28, v29
	s_waitcnt lgkmcnt(0)
	v_mfma_f32_32x32x16_bf16 v[36:51], v[8:11], v[84:87], v[36:51]
	ds_read_b64_tr_b16 v[8:9], v153 offset:128
	ds_read_b64_tr_b16 v[10:11], v153 offset:2688
	global_store_dwordx4 v[52:53], v[4:7], off
	ds_read_b64_tr_b16 v[24:25], v153 offset:5248
	ds_read_b64_tr_b16 v[26:27], v153 offset:7808
	v_cvt_pk_bf16_f32 v21, v30, v31
	v_cvt_pk_bf16_f32 v22, v32, v33
	v_cvt_pk_bf16_f32 v23, v34, v35
	global_store_dwordx4 v[52:53], v[20:23], off offset:16
	s_waitcnt lgkmcnt(2)
	v_mfma_f32_32x32x16_bf16 v[4:19], v[8:11], v[96:99], 0
	ds_read_b64_tr_b16 v[20:21], v153 offset:10368
	ds_read_b64_tr_b16 v[22:23], v153 offset:12928
	v_lshl_add_u64 v[28:29], v[120:121], 0, s[88:89]
	v_lshl_add_u64 v[52:53], v[28:29], 0, s[6:7]
	ds_read_b64_tr_b16 v[28:29], v153 offset:15488
	ds_read_b64_tr_b16 v[30:31], v153 offset:18048
	v_cvt_pk_bf16_f32 v36, v36, v37
	v_cvt_pk_bf16_f32 v37, v38, v39
	v_cvt_pk_bf16_f32 v38, v40, v41
	s_waitcnt lgkmcnt(4)
	v_mfma_f32_32x32x16_bf16 v[4:19], v[24:27], v[88:91], v[4:19]
	v_cvt_pk_bf16_f32 v24, v68, v69
	v_cvt_pk_bf16_f32 v25, v70, v71
	v_cvt_pk_bf16_f32 v26, v72, v73
	v_cvt_pk_bf16_f32 v27, v74, v75
	global_store_dwordx4 v[52:53], v[24:27], off
	ds_read_b64_tr_b16 v[24:25], v153 offset:192
	ds_read_b64_tr_b16 v[26:27], v153 offset:2752
	v_cvt_pk_bf16_f32 v39, v42, v43
	s_waitcnt lgkmcnt(4)
	v_mfma_f32_32x32x16_bf16 v[4:19], v[20:23], v[92:95], v[4:19]
	v_cvt_pk_bf16_f32 v20, v76, v77
	v_cvt_pk_bf16_f32 v21, v78, v79
	v_cvt_pk_bf16_f32 v22, v80, v81
	v_cvt_pk_bf16_f32 v23, v82, v83
	global_store_dwordx4 v[52:53], v[20:23], off offset:1024
	ds_read_b64_tr_b16 v[40:41], v153 offset:5312
	ds_read_b64_tr_b16 v[42:43], v153 offset:7872
	global_store_dwordx4 v[52:53], v[36:39], off offset:2048
	s_waitcnt lgkmcnt(4)
	v_mfma_f32_32x32x16_bf16 v[4:19], v[28:31], v[84:87], v[4:19]
	s_mul_i32 s6, s32, 0x200
	v_cvt_pk_bf16_f32 v36, v44, v45
	v_cvt_pk_bf16_f32 v37, v46, v47
	ds_read_b64_tr_b16 v[44:45], v153 offset:10432
	ds_read_b64_tr_b16 v[46:47], v153 offset:12992
	v_cvt_pk_bf16_f32 v38, v48, v49
	v_cvt_pk_bf16_f32 v39, v50, v51
	global_store_dwordx4 v[52:53], v[36:39], off offset:3072
	s_waitcnt lgkmcnt(4)
	v_mfma_f32_32x32x16_bf16 v[20:35], v[24:27], v[96:99], 0
	s_mov_b32 s7, 0
	s_nop 0
	v_cvt_pk_bf16_f32 v36, v4, v5
	v_cvt_pk_bf16_f32 v37, v6, v7
	ds_read_b64_tr_b16 v[4:5], v153 offset:15552
	ds_read_b64_tr_b16 v[6:7], v153 offset:18112
	v_cvt_pk_bf16_f32 v38, v8, v9
	v_add_co_u32_e64 v8, s[62:63], s97, v52
	s_waitcnt lgkmcnt(4)
	v_mfma_f32_32x32x16_bf16 v[20:35], v[40:43], v[88:91], v[20:35]
	v_addc_co_u32_e64 v9, s[62:63], 0, v53, s[62:63]
	v_cvt_pk_bf16_f32 v39, v10, v11
	v_cvt_pk_bf16_f32 v10, v12, v13
	v_cvt_pk_bf16_f32 v11, v14, v15
	v_cvt_pk_bf16_f32 v12, v16, v17
	v_cvt_pk_bf16_f32 v13, v18, v19
	s_waitcnt lgkmcnt(2)
	v_mfma_f32_32x32x16_bf16 v[20:35], v[44:47], v[92:95], v[20:35]
	v_lshl_add_u64 v[122:123], v[122:123], 0, s[6:7]
	s_mul_i32 s6, s32, 0x10000
	v_lshl_add_u64 v[120:121], v[120:121], 0, s[6:7]
	global_store_dwordx4 v[8:9], v[36:39], off
	global_store_dwordx4 v[8:9], v[10:13], off offset:1024
	s_waitcnt lgkmcnt(0)
	v_mfma_f32_32x32x16_bf16 v[20:35], v[4:7], v[84:87], v[20:35]
	s_nop 11
	v_cvt_pk_bf16_f32 v4, v20, v21
	v_cvt_pk_bf16_f32 v5, v22, v23
	v_cvt_pk_bf16_f32 v6, v24, v25
	v_cvt_pk_bf16_f32 v7, v26, v27
	global_store_dwordx4 v[8:9], v[4:7], off offset:2048
	s_nop 1
	v_cvt_pk_bf16_f32 v4, v28, v29
	v_cvt_pk_bf16_f32 v5, v30, v31
	v_cvt_pk_bf16_f32 v6, v32, v33
	v_cvt_pk_bf16_f32 v7, v34, v35
	global_store_dwordx4 v[8:9], v[4:7], off offset:3072
	s_barrier
; #define AIN(i) arg_in(i)
; __global__ void __launch_bounds__(NTHREADS, 2) fwd_megakernel(Args a) {
;     ...
;             for (int u = G - 1 - bx; u < nun; u += G) gla_a_unit(lds, PB, PB + PBE, FA, (unsigned char*)H, row0, (float*)((unsigned char*)H + WS_DECB), u >> 2, u & 3, AIN(10), AIN(11), tid);
	s_cbranch_scc1 .LBB0_564

; template <class Epi, class Sched, bool ALIGN_EPI = false, bool SP2 = false>
; __device__ __forceinline__ void gemm_phase(PG8_LAS unsigned char* lds, const Gemm g, const Sched& S, const Epi& E, const int tid_arg) {
;     ...
;         const bool has_next = S.next(ui + 1, nxt);
;         const char* nA = has_next ? (const char*)g.A + (size_t)nxt.pm * tstep : cA; const char* nB = has_next ? (const char*)g.Bt + (size_t)nxt.pn * tstep : cB;
;         for (int t = 0; t < nt; t += 2) {
;             const bool last = (t == nt - 2);
;             const char* a1 = cA + (size_t)(t + 1) * kstep;
;             const char* a2 = last ? nA : cA + (size_t)(t + 2) * kstep; const char* b2 = last ? nB : cB + (size_t)(t + 2) * kstep;
;             const char* a3 = a2 + kstep; const char* b3 = b2 + kstep;
;     ...
; #pragma unroll
;         for (int a = 0; a < 2; ++a)
; #pragma unroll
;             for (int b = 0; b < 2; ++b)
; #pragma unroll
;                 for (int m = 0; m < 4; ++m)
; #pragma unroll
;                     for (int n = 0; n < 2; ++n) acc[a][b][m][n] = (f32x4){0.f, 0.f, 0.f, 0.f};
;         cur = nxt; cA = nA; cB = nB; ++ui;
.LBB0_763:
	s_ashr_i32 s27, s26, 31
	s_lshl_b64 s[28:29], s[26:27], 19
	s_add_u32 s28, s3, s28
	s_addc_u32 s29, s6, s29
	s_and_b64 s[30:31], s[10:11], exec
	s_cselect_b32 s27, s29, s5
	s_cselect_b32 s48, s28, s4
	s_ashr_i32 s25, s24, 31
	s_lshl_b64 s[30:31], s[24:25], 19
	s_add_u32 s30, s7, s30
	s_addc_u32 s31, s38, s31
	s_and_b64 s[36:37], s[10:11], exec
	s_cselect_b32 s25, s31, s35
	s_cselect_b32 s49, s30, s34
	s_add_u32 s4, s4, 0x40080
	s_addc_u32 s5, s5, 0
	s_add_u32 s50, s34, 0x100
	v_mov_b32_e32 v4, 0
	s_addc_u32 s51, s35, 0
	s_mov_b32 s52, -2
	v_mov_b32_e32 v5, v4
	v_mov_b32_e32 v6, v4
	v_mov_b32_e32 v7, v4
	v_mov_b32_e32 v8, v4
	v_mov_b32_e32 v9, v4
	v_mov_b32_e32 v10, v4
	v_mov_b32_e32 v11, v4
	v_mov_b32_e32 v20, v4
	v_mov_b32_e32 v21, v4
	v_mov_b32_e32 v22, v4
	v_mov_b32_e32 v23, v4
	v_mov_b32_e32 v24, v4
	v_mov_b32_e32 v25, v4
	v_mov_b32_e32 v26, v4
	v_mov_b32_e32 v27, v4
	v_mov_b32_e32 v36, v4
	v_mov_b32_e32 v37, v4
	v_mov_b32_e32 v38, v4
	v_mov_b32_e32 v39, v4
	v_mov_b32_e32 v40, v4
	v_mov_b32_e32 v41, v4
	v_mov_b32_e32 v42, v4
	v_mov_b32_e32 v43, v4
	v_mov_b32_e32 v52, v4
	v_mov_b32_e32 v53, v4
	v_mov_b32_e32 v54, v4
	v_mov_b32_e32 v55, v4
	v_mov_b32_e32 v56, v4
	v_mov_b32_e32 v57, v4
	v_mov_b32_e32 v58, v4
	v_mov_b32_e32 v59, v4
	v_mov_b32_e32 v12, v4
	v_mov_b32_e32 v13, v4
	v_mov_b32_e32 v14, v4
	v_mov_b32_e32 v15, v4
	v_mov_b32_e32 v16, v4
	v_mov_b32_e32 v17, v4
	v_mov_b32_e32 v18, v4
	v_mov_b32_e32 v19, v4
	v_mov_b32_e32 v28, v4
	v_mov_b32_e32 v29, v4
	v_mov_b32_e32 v30, v4
	v_mov_b32_e32 v31, v4
	v_mov_b32_e32 v32, v4
	v_mov_b32_e32 v33, v4
	v_mov_b32_e32 v34, v4
	v_mov_b32_e32 v35, v4
	v_mov_b32_e32 v44, v4
	v_mov_b32_e32 v45, v4
	v_mov_b32_e32 v46, v4
	v_mov_b32_e32 v47, v4
	v_mov_b32_e32 v48, v4
	v_mov_b32_e32 v49, v4
	v_mov_b32_e32 v50, v4
	v_mov_b32_e32 v51, v4
	v_mov_b32_e32 v60, v4
	v_mov_b32_e32 v61, v4
	v_mov_b32_e32 v62, v4
	v_mov_b32_e32 v63, v4
	v_mov_b32_e32 v64, v4
	v_mov_b32_e32 v65, v4
	v_mov_b32_e32 v66, v4
	v_mov_b32_e32 v67, v4
	v_mov_b32_e32 v68, v4
	v_mov_b32_e32 v69, v4
	v_mov_b32_e32 v70, v4
	v_mov_b32_e32 v71, v4
	v_mov_b32_e32 v72, v4
	v_mov_b32_e32 v73, v4
	v_mov_b32_e32 v74, v4
	v_mov_b32_e32 v75, v4
	v_mov_b32_e32 v84, v4
	v_mov_b32_e32 v85, v4
	v_mov_b32_e32 v86, v4
	v_mov_b32_e32 v87, v4
	v_mov_b32_e32 v88, v4
	v_mov_b32_e32 v89, v4
	v_mov_b32_e32 v90, v4
	v_mov_b32_e32 v91, v4
	v_mov_b32_e32 v100, v4
	v_mov_b32_e32 v101, v4
	v_mov_b32_e32 v102, v4
	v_mov_b32_e32 v103, v4
	v_mov_b32_e32 v104, v4
	v_mov_b32_e32 v105, v4
	v_mov_b32_e32 v106, v4
	v_mov_b32_e32 v107, v4
	v_mov_b32_e32 v116, v4
	v_mov_b32_e32 v117, v4
	v_mov_b32_e32 v118, v4
	v_mov_b32_e32 v119, v4
	s_waitcnt vmcnt(0)
	v_mov_b32_e32 v120, v4
	v_mov_b32_e32 v121, v4
	v_mov_b32_e32 v122, v4
	v_mov_b32_e32 v123, v4
	v_mov_b32_e32 v76, v4
	v_mov_b32_e32 v77, v4
	v_mov_b32_e32 v78, v4
	v_mov_b32_e32 v79, v4
	v_mov_b32_e32 v80, v4
	v_mov_b32_e32 v81, v4
	v_mov_b32_e32 v82, v4
	v_mov_b32_e32 v83, v4
	v_mov_b32_e32 v92, v4
	v_mov_b32_e32 v93, v4
	v_mov_b32_e32 v94, v4
	v_mov_b32_e32 v95, v4
	v_mov_b32_e32 v96, v4
	v_mov_b32_e32 v97, v4
	v_mov_b32_e32 v98, v4
	v_mov_b32_e32 v99, v4
	v_mov_b32_e32 v108, v4
	v_mov_b32_e32 v109, v4
	v_mov_b32_e32 v110, v4
	v_mov_b32_e32 v111, v4
	v_mov_b32_e32 v112, v4
	v_mov_b32_e32 v113, v4
	v_mov_b32_e32 v114, v4
	v_mov_b32_e32 v115, v4
	v_mov_b32_e32 v124, v4
	v_mov_b32_e32 v125, v4
	v_mov_b32_e32 v126, v4
	v_mov_b32_e32 v127, v4
	v_mov_b32_e32 v128, v4
	v_mov_b32_e32 v129, v4
	v_mov_b32_e32 v130, v4
	v_mov_b32_e32 v131, v4
	s_nop 0
	s_nop 0
	s_nop 0
	s_nop 0
	s_nop 0
	s_nop 0
	s_nop 0
	s_nop 0
